# finalize_tile: second unrolled token-group copy (5.3 KB straight-line) replaced by a second pass over the first copy (loop-back stub renames 4 registers, replays the scalar epilogue)
# speedup vs baseline: 1.0054x; 1.0054x over previous
; #define LAS __attribute__((address_space(3)))
; DI void finalize_tile(const Params& p, int l, int tile, LAS unsigned char* lds, int tid, int lane, int wave, const bool doq = true) {
;     unsigned char* ws = p.ws;
;     const bf16_t* CQ = (const bf16_t*)(ws + WS_CQ); const bf16_t* MISC = (const bf16_t*)(ws + WS_MISC);
;     bf16_t* QR = (bf16_t*)(ws + WS_QR); const bf16_t* KVR = (const bf16_t*)(ws + WS_KVR); bf16_t* KB = (bf16_t*)(ws + WS_K); bf16_t* VT = (bf16_t*)(ws + WS_VT);
;     const float* COS = (const float*)(ws + WS_COS); const float* SIN = (const float*)(ws + WS_SIN);
;     LAS bf16_t* VL = (LAS bf16_t*)lds;
;     const int sub = lane >> 4, i = lane & 15;
;     const int t0 = tile * 64;
;     const float* qg = (const float*)(p.ws + WS_SM) + 1536 + l * 192; const float* kg = (const float*)(p.ws + WS_SM) + 2304 + l * 192;
; #pragma unroll
;     for (int it = 0; it < 2; ++it) {
;         const int tl = wave * 8 + it * 4 + sub; const size_t t = (size_t)(t0 + tl);
;         const u32x4 c0 = *(const u32x4*)(CQ + t * 256 + 16 * i), c1 = *(const u32x4*)(CQ + t * 256 + 16 * i + 8);
;         const u32x4 kvw = *(const u32x4*)(MISC + t * 256 + 8 * i);
;         const unsigned p1 = *(const unsigned*)(MISC + t * 256 + 128 + 2 * i), p2 = *(const unsigned*)(MISC + t * 256 + 160 + 2 * i);
;         const f32x2 cs = *(const f32x2*)(COS + t * 32 + 2 * i), sn = *(const f32x2*)(SIN + t * 32 + 2 * i);
;         float v[8], w[8]; float s1 = 0.f, s2 = 0.f;
;         unpack8(c0, v); unpack8(c1, w);
; #pragma unroll
;         for (int e = 0; e < 8; ++e) s1 += v[e] * v[e] + w[e] * w[e];
;         unpack8(kvw, v);
; #pragma unroll
;         for (int e = 0; e < 8; ++e) s2 += v[e] * v[e];
;         const float x1a = bflo(p1), x1b = bfhi(p1), x2a = bflo(p2), x2b = bfhi(p2);
;         float s3 = (x1a * x1a + x1b * x1b) + (x2a * x2a + x2b * x2b);
;         s1 = red16(s1, lane); s2 = red16(s2, lane); s3 = red16(s3, lane);
;         const float rcq = rsqrtf(s1 * (1.0f / 256.0f) + EPS), rckv = rsqrtf(s2 * (1.0f / 128.0f) + EPS);
;         u32x4 qa4[4], ka4[4], va4[4]; unsigned r14[4], r24[4];
; #pragma unroll
;         for (int h = 0; h < 4; ++h) { const bf16_t* qp = QR + t * 768 + h * 192; const bf16_t* kp = KVR + t * 1024 + h * 256;
;             qa4[h] = *(const u32x4*)(qp + 8 * i); r14[h] = *(const unsigned*)(qp + 128 + 2 * i); r24[h] = *(const unsigned*)(qp + 160 + 2 * i);
.LBB0_366:
	s_mov_b32 s98, 0
	s_mov_b32 s2, s33
	s_mov_b64 s[6:7], s[50:51]
	v_mbcnt_lo_u32_b32 v0, -1, 0
	v_mbcnt_hi_u32_b32 v0, -1, v0
	s_add_u32 s10, s6, 0x8e00000
	s_addc_u32 s11, s7, 0
	s_add_u32 s14, s6, 0x9600000
	s_addc_u32 s15, s7, 0
	s_add_u32 s8, s6, 0xae00000
	s_addc_u32 s9, s7, 0
	s_add_u32 s12, s6, 0xce00000
	s_addc_u32 s13, s7, 0
	s_add_u32 s3, s6, s4
	s_addc_u32 s17, s7, s5
	v_ashrrev_i32_e32 v2, 4, v0
	v_and_b32_e32 v16, 15, v0
	s_add_u32 s0, s3, 0x31800
	s_addc_u32 s1, s17, 0
	v_lshl_add_u32 v93, s2, 3, v2
	v_lshlrev_b32_e32 v2, 5, v16
	v_mov_b32_e32 v3, v1
	v_lshl_add_u32 v92, s2, 6, v0
	s_add_u32 s16, s3, 0x32400
	v_lshl_add_u64 v[4:5], s[6:7], 0, v[2:3]
	s_mov_b64 s[2:3], 0x8600000
	v_lshl_add_u64 v[52:53], v[4:5], 0, s[2:3]
	v_lshlrev_b32_e32 v4, 3, v16
	v_mov_b32_e32 v5, v1
	v_add_u32_e32 v58, s19, v93
	v_lshl_add_u64 v[6:7], s[6:7], 0, v[4:5]
	s_mov_b64 s[2:3], 0x2100000
	v_ashrrev_i32_e32 v59, 31, v58
	v_lshl_add_u64 v[54:55], v[6:7], 0, s[2:3]
	s_mov_b64 s[2:3], 0x2300000
	v_lshlrev_b64 v[10:11], 9, v[58:59]
	s_addc_u32 s17, s17, 0
	v_lshl_add_u64 v[56:57], v[6:7], 0, s[2:3]
	v_lshl_add_u64 v[6:7], v[52:53], 0, v[10:11]
	v_lshl_add_u64 v[66:67], s[0:1], 0, v[2:3]
	v_lshl_add_u64 v[64:65], s[16:17], 0, v[2:3]
	v_lshl_add_u64 v[62:63], s[0:1], 0, v[4:5]
	v_lshl_add_u64 v[60:61], s[16:17], 0, v[4:5]
.Lfin_P:
	flat_load_dwordx4 v[2:5], v[6:7]
	s_nop 0
	flat_load_dwordx4 v[6:9], v[6:7] offset:16
	v_lshlrev_b32_e32 v0, 4, v16
	v_lshl_add_u64 v[14:15], s[10:11], 0, v[10:11]
	v_lshl_add_u64 v[10:11], v[14:15], 0, v[0:1]
	flat_load_dwordx4 v[10:13], v[10:11]
	v_lshlrev_b32_e32 v50, 2, v16
	v_mov_b32_e32 v51, v1
	v_lshl_add_u64 v[14:15], v[14:15], 0, v[50:51]
	s_waitcnt vmcnt(0)
	flat_load_dword v18, v[14:15] offset:256
	flat_load_dword v19, v[14:15] offset:320
	v_lshlrev_b64 v[14:15], 7, v[58:59]
	v_lshl_add_u64 v[16:17], v[54:55], 0, v[14:15]
	v_lshl_add_u64 v[14:15], v[56:57], 0, v[14:15]
	flat_load_dwordx2 v[72:73], v[16:17]
	flat_load_dwordx2 v[74:75], v[14:15]
	v_mov_b64_e32 v[68:69], s[14:15]
	s_add_i32 s22, s22, s68
	s_waitcnt lgkmcnt(0)
	v_lshlrev_b32_e32 v20, 16, v2
	v_and_b32_e32 v21, 0xffff0000, v2
	v_lshlrev_b32_e32 v15, 16, v3
	v_and_b32_e32 v14, 0xffff0000, v3
	v_lshlrev_b32_e32 v3, 16, v4
	v_and_b32_e32 v2, 0xffff0000, v4
	v_lshlrev_b32_e32 v4, 16, v6
	v_and_b32_e32 v22, 0xffff0000, v6
	v_lshlrev_b32_e32 v17, 16, v7
	v_and_b32_e32 v16, 0xffff0000, v7
	v_lshlrev_b32_e32 v7, 16, v8
	v_and_b32_e32 v6, 0xffff0000, v8
	v_pk_mul_f32 v[6:7], v[6:7], v[6:7]
	v_mul_f32_e32 v8, v4, v4
	v_pk_fma_f32 v[2:3], v[2:3], v[2:3], v[6:7]
	v_and_b32_e32 v6, 0xffff0000, v9
	v_lshlrev_b32_e32 v7, 16, v9
	v_and_b32_e32 v4, 0xffff0000, v5
	v_lshlrev_b32_e32 v5, 16, v5
	v_pk_mul_f32 v[6:7], v[6:7], v[6:7]
	v_mul_f32_e32 v22, v22, v22
	v_pk_fma_f32 v[4:5], v[4:5], v[4:5], v[6:7]
	v_and_b32_e32 v7, 0xffff0000, v10
	v_lshlrev_b32_e32 v6, 16, v10
	v_mul_f32_e32 v9, v7, v7
	v_fmac_f32_e32 v9, v6, v6
	v_and_b32_e32 v6, 0xffff0000, v11
	v_lshlrev_b32_e32 v7, 16, v11
	v_pk_mul_f32 v[6:7], v[6:7], v[6:7]
	v_fmac_f32_e32 v22, v21, v21
	v_add_f32_e32 v7, v7, v9
	v_add_f32_e32 v9, v6, v7
	v_and_b32_e32 v6, 0xffff0000, v12
	v_lshlrev_b32_e32 v7, 16, v12
	v_pk_mul_f32 v[6:7], v[6:7], v[6:7]
	v_pk_mul_f32 v[16:17], v[16:17], v[16:17]
	v_add_f32_e32 v7, v7, v9
	v_add_f32_e32 v9, v6, v7
	v_and_b32_e32 v6, 0xffff0000, v13
	v_lshlrev_b32_e32 v7, 16, v13
	v_pk_mul_f32 v[6:7], v[6:7], v[6:7]
	v_fmac_f32_e32 v8, v20, v20
	v_add_f32_e32 v7, v7, v9
	v_pk_fma_f32 v[14:15], v[14:15], v[14:15], v[16:17]
	v_add_f32_e32 v6, v6, v7
	v_add_f32_e32 v7, v8, v22
	v_add_f32_e32 v7, v15, v7
	v_add_f32_e32 v7, v14, v7
	v_add_f32_e32 v3, v3, v7
	v_add_f32_e32 v2, v2, v3
	v_add_f32_e32 v2, v5, v2
	s_waitcnt vmcnt(0)
	v_and_b32_e32 v79, 0xffff0000, v19
	v_add_f32_e32 v3, v4, v2
	v_lshlrev_b32_e32 v78, 16, v19
	v_mul_f32_e32 v2, v79, v79
	v_pk_fma_f32 v[86:87], v[78:79], v[78:79], v[2:3] op_sel_hi:[1,1,0]
	v_lshlrev_b32_e32 v76, 16, v18
	v_add_f32_dpp v2, v3, v3 row_ror:1 row_mask:0xf bank_mask:0xf bound_ctrl:1
	v_add_f32_dpp v3, v6, v6 row_ror:1 row_mask:0xf bank_mask:0xf bound_ctrl:1
	v_and_b32_e32 v77, 0xffff0000, v18
	v_add_f32_dpp v2, v2, v2 row_ror:2 row_mask:0xf bank_mask:0xf bound_ctrl:1
	v_add_f32_dpp v3, v3, v3 row_ror:2 row_mask:0xf bank_mask:0xf bound_ctrl:1
	s_nop 0
	v_add_f32_dpp v2, v2, v2 row_ror:4 row_mask:0xf bank_mask:0xf bound_ctrl:1
	v_add_f32_dpp v3, v3, v3 row_ror:4 row_mask:0xf bank_mask:0xf bound_ctrl:1
	s_nop 0
	v_add_f32_dpp v2, v2, v2 row_ror:8 row_mask:0xf bank_mask:0xf bound_ctrl:1
	v_fmamk_f32 v2, v2, 0x3b800000, v228
	v_cmp_gt_f32_e64 s[0:1], s95, v2
	v_mul_f32_e32 v4, 0x4b800000, v2
	v_add_f32_dpp v3, v3, v3 row_ror:8 row_mask:0xf bank_mask:0xf bound_ctrl:1
	v_cndmask_b32_e64 v2, v2, v4, s[0:1]
	v_rsq_f32_e32 v6, v2
	v_fmamk_f32 v2, v3, 0x3c000000, v228
	v_cmp_gt_f32_e32 vcc, s95, v2
	v_mul_f32_e32 v3, 0x4b800000, v2
	v_lshlrev_b64 v[4:5], 11, v[58:59]
	v_cndmask_b32_e32 v2, v2, v3, vcc
	v_rsq_f32_e32 v87, v2
	v_mad_i64_i32 v[2:3], s[2:3], v58, s76, v[68:69]
	v_lshl_add_u64 v[84:85], v[2:3], 0, v[0:1]
	v_lshl_add_u64 v[70:71], v[2:3], 0, v[50:51]
	flat_load_dwordx4 v[94:97], v[84:85]
	flat_load_dword v59, v[70:71] offset:256
	flat_load_dword v111, v[70:71] offset:320
	v_lshl_add_u64 v[4:5], s[8:9], 0, v[4:5]
	v_mul_f32_e32 v7, 0x45800000, v6
	v_lshl_add_u64 v[2:3], v[4:5], 0, v[0:1]
	flat_load_dwordx4 v[38:41], v[2:3]
	flat_load_dwordx4 v[34:37], v[2:3] offset:256
	flat_load_dwordx4 v[98:101], v[84:85] offset:384
	flat_load_dword v133, v[70:71] offset:640
	flat_load_dword v134, v[70:71] offset:704
	flat_load_dwordx4 v[30:33], v[2:3] offset:512
	flat_load_dwordx4 v[26:29], v[2:3] offset:768
	flat_load_dwordx4 v[102:105], v[84:85] offset:768
	flat_load_dword v135, v[70:71] offset:1024
	flat_load_dword v136, v[70:71] offset:1088
	flat_load_dwordx4 v[22:25], v[2:3] offset:1024
	flat_load_dwordx4 v[18:21], v[2:3] offset:1280
	flat_load_dwordx4 v[106:109], v[84:85] offset:1152
	flat_load_dword v137, v[70:71] offset:1408
	flat_load_dword v138, v[70:71] offset:1472
	flat_load_dwordx4 v[14:17], v[2:3] offset:1536
	s_nop 0
	flat_load_dwordx4 v[2:5], v[2:3] offset:1792
	v_cndmask_b32_e64 v110, v6, v7, s[0:1]
	flat_load_dwordx4 v[46:49], v[66:67]
	flat_load_dwordx4 v[42:45], v[66:67] offset:16
	flat_load_dwordx4 v[10:13], v[64:65]
	flat_load_dwordx4 v[6:9], v[64:65] offset:16
	flat_load_dwordx2 v[90:91], v[62:63] offset:512
	flat_load_dwordx2 v[88:89], v[62:63] offset:640
	flat_load_dwordx2 v[82:83], v[60:61] offset:512
	flat_load_dwordx2 v[80:81], v[60:61] offset:640
	v_mul_f32_e32 v132, 0x45800000, v87
	s_waitcnt vmcnt(0) lgkmcnt(0)
; DI unsigned pk2(float lo, float hi) { f32x2 v = {lo, hi}; return __builtin_bit_cast(unsigned, __builtin_convertvector(v, bf2_t)); }
; DI float bflo(unsigned w) { return __uint_as_float(w << 16); }
; DI float bfhi(unsigned w) { return __uint_as_float(w & 0xffff0000u); }
; DI float red16(float v, int lane) { (void)lane; v += DPP_ROR(v, 1); v += DPP_ROR(v, 2); v += DPP_ROR(v, 4); v += DPP_ROR(v, 8); return v; }
; DI void unpack8(const u32x4 w, float (&v)[8]) { v[0] = bflo(w.x); v[1] = bfhi(w.x); v[2] = bflo(w.y); v[3] = bfhi(w.y); v[4] = bflo(w.z); v[5] = bfhi(w.z); v[6] = bflo(w.w); v[7] = bfhi(w.w); }
; DI void finalize_tile(const Params& p, int l, int tile, LAS unsigned char* lds, int tid, int lane, int wave, const bool doq = true) {
;     ...
;         if (doq)
; #pragma unroll
;         for (int h = 0; h < 4; ++h) {
;             bf16_t* qp = QR + t * 768 + h * 192;
;             const u32x4 qa = qa4[h]; const unsigned r1 = r14[h], r2 = r24[h];
;             unpack8(qa, v);
;             const float y1a = bflo(r1) * rcq, y1b = bfhi(r1) * rcq, y2a = bflo(r2) * rcq, y2b = bfhi(r2) * rcq;
;             float ss = (y1a * y1a + y1b * y1b) + (y2a * y2a + y2b * y2b);
; #pragma unroll
;             for (int e = 0; e < 8; ++e) { v[e] *= rcq; ss += v[e] * v[e]; }
;             ss = red16(ss, lane);
;             const float rq = rsqrtf(ss * (1.0f / 192.0f) + EPS) * QSCALE;
;             const f32x4 g0 = qg0, g1 = qg1; const f32x2 gr1 = qgr1, gr2 = qgr2;
;             u32x4 o; o.x = pk2(v[0] * rq * g0.x, v[1] * rq * g0.y); o.y = pk2(v[2] * rq * g0.z, v[3] * rq * g0.w); o.z = pk2(v[4] * rq * g1.x, v[5] * rq * g1.y); o.w = pk2(v[6] * rq * g1.z, v[7] * rq * g1.w);
;             *(u32x4*)(qp + 8 * i) = o;
;             const float a1 = y1a * rq * gr1.x, b1 = y1b * rq * gr1.y, a2 = y2a * rq * gr2.x, b2 = y2b * rq * gr2.y;
;             *(unsigned*)(qp + 128 + 2 * i) = pk2(a1 * cs.x - a2 * sn.x, b1 * cs.y - b2 * sn.y);
;             *(unsigned*)(qp + 160 + 2 * i) = pk2(a1 * sn.x + a2 * cs.x, b1 * sn.y + b2 * cs.y);
;         }
	v_lshlrev_b32_e32 v112, 16, v59
	v_and_b32_e32 v113, 0xffff0000, v59
	v_lshlrev_b32_e32 v114, 16, v111
	v_and_b32_e32 v115, 0xffff0000, v111
	v_pk_mul_f32 v[112:113], v[110:111], v[112:113] op_sel_hi:[0,1]
	v_pk_mul_f32 v[114:115], v[110:111], v[114:115] op_sel_hi:[0,1]
	v_lshlrev_b32_e32 v116, 16, v97
	v_and_b32_e32 v117, 0xffff0000, v97
	v_lshlrev_b32_e32 v120, 16, v96
	v_and_b32_e32 v121, 0xffff0000, v96
	v_lshlrev_b32_e32 v122, 16, v95
	v_and_b32_e32 v123, 0xffff0000, v95
	v_lshlrev_b32_e32 v126, 16, v94
	v_and_b32_e32 v127, 0xffff0000, v94
	v_pk_mul_f32 v[128:129], v[112:113], v[112:113]
	v_pk_mul_f32 v[130:131], v[114:115], v[114:115]
	v_pk_mul_f32 v[116:117], v[110:111], v[116:117] op_sel_hi:[0,1]
	v_pk_mul_f32 v[96:97], v[110:111], v[120:121] op_sel_hi:[0,1]
	v_pk_mul_f32 v[122:123], v[110:111], v[122:123] op_sel_hi:[0,1]
	v_pk_mul_f32 v[94:95], v[110:111], v[126:127] op_sel_hi:[0,1]
	v_add_f32_e32 v59, v130, v131
	v_add_f32_e32 v111, v128, v129
	v_pk_mul_f32 v[126:127], v[94:95], v[94:95]
	v_add_f32_e32 v59, v111, v59
	v_add_f32_e32 v59, v126, v59
	v_pk_mul_f32 v[124:125], v[122:123], v[122:123]
	v_add_f32_e32 v59, v127, v59
	v_add_f32_e32 v59, v124, v59
	v_pk_mul_f32 v[120:121], v[96:97], v[96:97]
	v_add_f32_e32 v59, v125, v59
	v_add_f32_e32 v59, v120, v59
	v_pk_mul_f32 v[118:119], v[116:117], v[116:117]
	v_add_f32_e32 v59, v121, v59
	v_add_f32_e32 v59, v118, v59
	v_add_f32_e32 v59, v119, v59
	s_nop 1
	v_add_f32_dpp v59, v59, v59 row_ror:1 row_mask:0xf bank_mask:0xf bound_ctrl:1
	s_nop 1
	v_add_f32_dpp v59, v59, v59 row_ror:2 row_mask:0xf bank_mask:0xf bound_ctrl:1
	s_nop 1
	v_add_f32_dpp v59, v59, v59 row_ror:4 row_mask:0xf bank_mask:0xf bound_ctrl:1
	s_nop 1
	v_add_f32_dpp v59, v59, v59 row_ror:8 row_mask:0xf bank_mask:0xf bound_ctrl:1
	v_fmamk_f32 v59, v59, 0x3baaaaab, v228
	v_cmp_gt_f32_e64 s[0:1], s95, v59
	v_mul_f32_e32 v111, 0x4b800000, v59
	s_nop 0
	v_cndmask_b32_e64 v59, v59, v111, s[0:1]
	v_rsq_f32_e32 v59, v59
	s_nop 0
	v_mul_f32_e32 v111, 0x45800000, v59
	v_cndmask_b32_e64 v59, v59, v111, s[0:1]
	v_mul_f32_e32 v118, 0x3dd53b94, v59
	v_pk_mul_f32 v[94:95], v[94:95], v[118:119] op_sel_hi:[1,0]
	v_pk_mul_f32 v[120:121], v[122:123], v[118:119] op_sel_hi:[1,0]
	v_pk_mul_f32 v[96:97], v[96:97], v[118:119] op_sel_hi:[1,0]
	v_pk_mul_f32 v[116:117], v[116:117], v[118:119] op_sel_hi:[1,0]
	v_pk_mul_f32 v[94:95], v[46:47], v[94:95]
	v_pk_mul_f32 v[120:121], v[48:49], v[120:121]
	v_pk_mul_f32 v[96:97], v[42:43], v[96:97]
	v_pk_mul_f32 v[116:117], v[44:45], v[116:117]
	v_cvt_pk_bf16_f32 v94, v94, v95
	v_cvt_pk_bf16_f32 v95, v120, v121
	v_cvt_pk_bf16_f32 v96, v96, v97
	v_cvt_pk_bf16_f32 v97, v116, v117
	flat_store_dwordx4 v[84:85], v[94:97]
	v_lshlrev_b32_e32 v122, 16, v98
	v_and_b32_e32 v123, 0xffff0000, v98
	v_pk_mul_f32 v[96:97], v[114:115], v[118:119] op_sel_hi:[1,0]
	v_pk_mul_f32 v[94:95], v[112:113], v[118:119] op_sel_hi:[1,0]
	v_pk_mul_f32 v[96:97], v[88:89], v[96:97]
	v_pk_mul_f32 v[94:95], v[90:91], v[94:95]
	v_pk_mul_f32 v[112:113], v[74:75], v[96:97]
	v_pk_mul_f32 v[96:97], v[72:73], v[96:97]
	v_pk_fma_f32 v[112:113], v[72:73], v[94:95], v[112:113] neg_lo:[0,0,1] neg_hi:[0,0,1]
	v_pk_fma_f32 v[94:95], v[74:75], v[94:95], v[96:97]
	v_cvt_pk_bf16_f32 v59, v112, v113
	flat_store_dword v[70:71], v59 offset:256
	v_cvt_pk_bf16_f32 v59, v94, v95
	v_lshlrev_b32_e32 v94, 16, v133
	v_and_b32_e32 v95, 0xffff0000, v133
	v_lshlrev_b32_e32 v96, 16, v134
	v_and_b32_e32 v97, 0xffff0000, v134
	v_pk_mul_f32 v[124:125], v[110:111], v[94:95] op_sel_hi:[0,1]
	v_pk_mul_f32 v[126:127], v[110:111], v[96:97] op_sel_hi:[0,1]
	v_pk_mul_f32 v[94:95], v[124:125], v[124:125]
	v_pk_mul_f32 v[96:97], v[126:127], v[126:127]
	flat_store_dword v[70:71], v59 offset:320
	v_lshlrev_b32_e32 v118, 16, v99
	v_and_b32_e32 v119, 0xffff0000, v99
	v_pk_mul_f32 v[98:99], v[110:111], v[122:123] op_sel_hi:[0,1]
	v_add_f32_e32 v59, v96, v97
	v_add_f32_e32 v94, v94, v95
	v_pk_mul_f32 v[122:123], v[98:99], v[98:99]
	v_add_f32_e32 v59, v94, v59
	v_pk_mul_f32 v[118:119], v[110:111], v[118:119] op_sel_hi:[0,1]
	v_add_f32_e32 v59, v122, v59
	v_lshlrev_b32_e32 v116, 16, v100
	v_and_b32_e32 v117, 0xffff0000, v100
	v_pk_mul_f32 v[120:121], v[118:119], v[118:119]
	v_add_f32_e32 v59, v123, v59
	v_lshlrev_b32_e32 v112, 16, v101
	v_and_b32_e32 v113, 0xffff0000, v101
	v_pk_mul_f32 v[100:101], v[110:111], v[116:117] op_sel_hi:[0,1]
	v_add_f32_e32 v59, v120, v59
	v_pk_mul_f32 v[116:117], v[100:101], v[100:101]
	v_add_f32_e32 v59, v121, v59
	v_pk_mul_f32 v[112:113], v[110:111], v[112:113] op_sel_hi:[0,1]
	v_add_f32_e32 v59, v116, v59
	v_pk_mul_f32 v[114:115], v[112:113], v[112:113]
	v_add_f32_e32 v59, v117, v59
	v_add_f32_e32 v59, v114, v59
	v_add_f32_e32 v59, v115, v59
	s_nop 1
	v_add_f32_dpp v59, v59, v59 row_ror:1 row_mask:0xf bank_mask:0xf bound_ctrl:1
	s_nop 1
	v_add_f32_dpp v59, v59, v59 row_ror:2 row_mask:0xf bank_mask:0xf bound_ctrl:1
	s_nop 1
	v_add_f32_dpp v59, v59, v59 row_ror:4 row_mask:0xf bank_mask:0xf bound_ctrl:1
	s_nop 1
	v_add_f32_dpp v59, v59, v59 row_ror:8 row_mask:0xf bank_mask:0xf bound_ctrl:1
	v_fmamk_f32 v59, v59, 0x3baaaaab, v228
	v_cmp_gt_f32_e64 s[0:1], s95, v59
	v_mul_f32_e32 v94, 0x4b800000, v59
	s_nop 0
	v_cndmask_b32_e64 v59, v59, v94, s[0:1]
	v_rsq_f32_e32 v59, v59
	s_nop 0
	v_mul_f32_e32 v94, 0x45800000, v59
	v_cndmask_b32_e64 v59, v59, v94, s[0:1]
	v_mul_f32_e32 v114, 0x3dd53b94, v59
	v_pk_mul_f32 v[94:95], v[98:99], v[114:115] op_sel_hi:[1,0]
	v_pk_mul_f32 v[96:97], v[118:119], v[114:115] op_sel_hi:[1,0]
	v_pk_mul_f32 v[94:95], v[46:47], v[94:95]
	v_pk_mul_f32 v[96:97], v[48:49], v[96:97]
	v_cvt_pk_bf16_f32 v94, v94, v95
	v_cvt_pk_bf16_f32 v95, v96, v97
; DI unsigned pk2(float lo, float hi) { f32x2 v = {lo, hi}; return __builtin_bit_cast(unsigned, __builtin_convertvector(v, bf2_t)); }
; DI float bflo(unsigned w) { return __uint_as_float(w << 16); }
; DI float bfhi(unsigned w) { return __uint_as_float(w & 0xffff0000u); }
; DI float red16(float v, int lane) { (void)lane; v += DPP_ROR(v, 1); v += DPP_ROR(v, 2); v += DPP_ROR(v, 4); v += DPP_ROR(v, 8); return v; }
; DI void unpack8(const u32x4 w, float (&v)[8]) { v[0] = bflo(w.x); v[1] = bfhi(w.x); v[2] = bflo(w.y); v[3] = bfhi(w.y); v[4] = bflo(w.z); v[5] = bfhi(w.z); v[6] = bflo(w.w); v[7] = bfhi(w.w); }
; DI void finalize_tile(const Params& p, int l, int tile, LAS unsigned char* lds, int tid, int lane, int wave, const bool doq = true) {
;     ...
;         if (doq)
; #pragma unroll
;         for (int h = 0; h < 4; ++h) {
;             bf16_t* qp = QR + t * 768 + h * 192;
;             const u32x4 qa = qa4[h]; const unsigned r1 = r14[h], r2 = r24[h];
;             unpack8(qa, v);
;             const float y1a = bflo(r1) * rcq, y1b = bfhi(r1) * rcq, y2a = bflo(r2) * rcq, y2b = bfhi(r2) * rcq;
;             float ss = (y1a * y1a + y1b * y1b) + (y2a * y2a + y2b * y2b);
; #pragma unroll
;             for (int e = 0; e < 8; ++e) { v[e] *= rcq; ss += v[e] * v[e]; }
;             ss = red16(ss, lane);
;             const float rq = rsqrtf(ss * (1.0f / 192.0f) + EPS) * QSCALE;
;             const f32x4 g0 = qg0, g1 = qg1; const f32x2 gr1 = qgr1, gr2 = qgr2;
;             u32x4 o; o.x = pk2(v[0] * rq * g0.x, v[1] * rq * g0.y); o.y = pk2(v[2] * rq * g0.z, v[3] * rq * g0.w); o.z = pk2(v[4] * rq * g1.x, v[5] * rq * g1.y); o.w = pk2(v[6] * rq * g1.z, v[7] * rq * g1.w);
;             *(u32x4*)(qp + 8 * i) = o;
;             const float a1 = y1a * rq * gr1.x, b1 = y1b * rq * gr1.y, a2 = y2a * rq * gr2.x, b2 = y2b * rq * gr2.y;
;             *(unsigned*)(qp + 128 + 2 * i) = pk2(a1 * cs.x - a2 * sn.x, b1 * cs.y - b2 * sn.y);
;             *(unsigned*)(qp + 160 + 2 * i) = pk2(a1 * sn.x + a2 * cs.x, b1 * sn.y + b2 * cs.y);
;         }
	v_pk_mul_f32 v[96:97], v[100:101], v[114:115] op_sel_hi:[1,0]
	v_pk_mul_f32 v[98:99], v[112:113], v[114:115] op_sel_hi:[1,0]
	v_pk_mul_f32 v[96:97], v[42:43], v[96:97]
	v_pk_mul_f32 v[98:99], v[44:45], v[98:99]
	v_cvt_pk_bf16_f32 v96, v96, v97
	v_cvt_pk_bf16_f32 v97, v98, v99
	flat_store_dwordx4 v[84:85], v[94:97] offset:384
	v_lshlrev_b32_e32 v118, 16, v102
	v_and_b32_e32 v119, 0xffff0000, v102
	v_pk_mul_f32 v[96:97], v[126:127], v[114:115] op_sel_hi:[1,0]
	v_pk_mul_f32 v[94:95], v[124:125], v[114:115] op_sel_hi:[1,0]
	v_pk_mul_f32 v[96:97], v[88:89], v[96:97]
	v_pk_mul_f32 v[94:95], v[90:91], v[94:95]
	v_pk_mul_f32 v[98:99], v[74:75], v[96:97]
	v_pk_mul_f32 v[96:97], v[72:73], v[96:97]
	v_pk_fma_f32 v[98:99], v[72:73], v[94:95], v[98:99] neg_lo:[0,0,1] neg_hi:[0,0,1]
	v_pk_fma_f32 v[94:95], v[74:75], v[94:95], v[96:97]
	v_cvt_pk_bf16_f32 v59, v98, v99
	flat_store_dword v[70:71], v59 offset:640
	v_cvt_pk_bf16_f32 v59, v94, v95
	v_lshlrev_b32_e32 v94, 16, v135
	v_and_b32_e32 v95, 0xffff0000, v135
	v_lshlrev_b32_e32 v96, 16, v136
	v_and_b32_e32 v97, 0xffff0000, v136
	v_pk_mul_f32 v[120:121], v[110:111], v[94:95] op_sel_hi:[0,1]
	v_pk_mul_f32 v[122:123], v[110:111], v[96:97] op_sel_hi:[0,1]
	v_pk_mul_f32 v[94:95], v[120:121], v[120:121]
	v_pk_mul_f32 v[96:97], v[122:123], v[122:123]
	flat_store_dword v[70:71], v59 offset:704
	v_lshlrev_b32_e32 v114, 16, v103
	v_and_b32_e32 v115, 0xffff0000, v103
	v_pk_mul_f32 v[102:103], v[110:111], v[118:119] op_sel_hi:[0,1]
	v_add_f32_e32 v59, v96, v97
	v_add_f32_e32 v94, v94, v95
	v_pk_mul_f32 v[118:119], v[102:103], v[102:103]
	v_add_f32_e32 v59, v94, v59
	v_pk_mul_f32 v[114:115], v[110:111], v[114:115] op_sel_hi:[0,1]
	v_add_f32_e32 v59, v118, v59
	v_lshlrev_b32_e32 v112, 16, v104
	v_and_b32_e32 v113, 0xffff0000, v104
	v_pk_mul_f32 v[116:117], v[114:115], v[114:115]
	v_add_f32_e32 v59, v119, v59
	v_lshlrev_b32_e32 v98, 16, v105
	v_and_b32_e32 v99, 0xffff0000, v105
	v_pk_mul_f32 v[104:105], v[110:111], v[112:113] op_sel_hi:[0,1]
	v_add_f32_e32 v59, v116, v59
	v_pk_mul_f32 v[112:113], v[104:105], v[104:105]
	v_add_f32_e32 v59, v117, v59
	v_pk_mul_f32 v[98:99], v[110:111], v[98:99] op_sel_hi:[0,1]
	v_add_f32_e32 v59, v112, v59
	v_pk_mul_f32 v[100:101], v[98:99], v[98:99]
	v_add_f32_e32 v59, v113, v59
	v_add_f32_e32 v59, v100, v59
	v_add_f32_e32 v59, v101, v59
	s_nop 1
	v_add_f32_dpp v59, v59, v59 row_ror:1 row_mask:0xf bank_mask:0xf bound_ctrl:1
	s_nop 1
	v_add_f32_dpp v59, v59, v59 row_ror:2 row_mask:0xf bank_mask:0xf bound_ctrl:1
	s_nop 1
	v_add_f32_dpp v59, v59, v59 row_ror:4 row_mask:0xf bank_mask:0xf bound_ctrl:1
	s_nop 1
	v_add_f32_dpp v59, v59, v59 row_ror:8 row_mask:0xf bank_mask:0xf bound_ctrl:1
	v_fmamk_f32 v59, v59, 0x3baaaaab, v228
	v_cmp_gt_f32_e64 s[0:1], s95, v59
	v_mul_f32_e32 v94, 0x4b800000, v59
	s_nop 0
	v_cndmask_b32_e64 v59, v59, v94, s[0:1]
	v_rsq_f32_e32 v59, v59
	s_nop 0
	v_mul_f32_e32 v94, 0x45800000, v59
	v_cndmask_b32_e64 v59, v59, v94, s[0:1]
	v_mul_f32_e32 v100, 0x3dd53b94, v59
	v_pk_mul_f32 v[94:95], v[102:103], v[100:101] op_sel_hi:[1,0]
	v_pk_mul_f32 v[96:97], v[114:115], v[100:101] op_sel_hi:[1,0]
	v_pk_mul_f32 v[94:95], v[46:47], v[94:95]
	v_pk_mul_f32 v[96:97], v[48:49], v[96:97]
	v_cvt_pk_bf16_f32 v94, v94, v95
	v_cvt_pk_bf16_f32 v95, v96, v97
	v_pk_mul_f32 v[96:97], v[104:105], v[100:101] op_sel_hi:[1,0]
	v_pk_mul_f32 v[98:99], v[98:99], v[100:101] op_sel_hi:[1,0]
	v_pk_mul_f32 v[96:97], v[42:43], v[96:97]
	v_pk_mul_f32 v[98:99], v[44:45], v[98:99]
	v_cvt_pk_bf16_f32 v96, v96, v97
	v_cvt_pk_bf16_f32 v97, v98, v99
	flat_store_dwordx4 v[84:85], v[94:97] offset:768
	v_lshlrev_b32_e32 v102, 16, v108
	v_and_b32_e32 v103, 0xffff0000, v108
	v_pk_mul_f32 v[96:97], v[122:123], v[100:101] op_sel_hi:[1,0]
	v_pk_mul_f32 v[94:95], v[120:121], v[100:101] op_sel_hi:[1,0]
	v_pk_mul_f32 v[96:97], v[88:89], v[96:97]
	v_pk_mul_f32 v[94:95], v[90:91], v[94:95]
	v_pk_mul_f32 v[98:99], v[74:75], v[96:97]
	v_pk_mul_f32 v[96:97], v[72:73], v[96:97]
	v_pk_fma_f32 v[98:99], v[72:73], v[94:95], v[98:99] neg_lo:[0,0,1] neg_hi:[0,0,1]
	v_pk_fma_f32 v[94:95], v[74:75], v[94:95], v[96:97]
	v_cvt_pk_bf16_f32 v59, v98, v99
	flat_store_dword v[70:71], v59 offset:1024
	v_cvt_pk_bf16_f32 v59, v94, v95
	v_lshlrev_b32_e32 v94, 16, v137
	v_and_b32_e32 v95, 0xffff0000, v137
	v_lshlrev_b32_e32 v96, 16, v138
	v_and_b32_e32 v97, 0xffff0000, v138
	v_lshlrev_b32_e32 v98, 16, v109
	v_and_b32_e32 v99, 0xffff0000, v109
	v_lshlrev_b32_e32 v108, 16, v107
	v_and_b32_e32 v109, 0xffff0000, v107
	v_lshlrev_b32_e32 v114, 16, v106
	v_and_b32_e32 v115, 0xffff0000, v106
	v_pk_mul_f32 v[94:95], v[110:111], v[94:95] op_sel_hi:[0,1]
	v_pk_mul_f32 v[96:97], v[110:111], v[96:97] op_sel_hi:[0,1]
	v_pk_mul_f32 v[98:99], v[110:111], v[98:99] op_sel_hi:[0,1]
	v_pk_mul_f32 v[102:103], v[110:111], v[102:103] op_sel_hi:[0,1]
	v_pk_mul_f32 v[108:109], v[110:111], v[108:109] op_sel_hi:[0,1]
	v_pk_mul_f32 v[106:107], v[110:111], v[114:115] op_sel_hi:[0,1]
	v_pk_mul_f32 v[110:111], v[94:95], v[94:95]
	v_pk_mul_f32 v[116:117], v[96:97], v[96:97]
	flat_store_dword v[70:71], v59 offset:1088
	v_add_f32_e32 v59, v116, v117
	v_add_f32_e32 v110, v110, v111
	v_pk_mul_f32 v[114:115], v[106:107], v[106:107]
	v_add_f32_e32 v59, v110, v59
	v_add_f32_e32 v59, v114, v59
	v_pk_mul_f32 v[112:113], v[108:109], v[108:109]
	v_add_f32_e32 v59, v115, v59
	v_add_f32_e32 v59, v112, v59
	v_pk_mul_f32 v[104:105], v[102:103], v[102:103]
	v_add_f32_e32 v59, v113, v59
	v_add_f32_e32 v59, v104, v59
	v_pk_mul_f32 v[100:101], v[98:99], v[98:99]
	v_add_f32_e32 v59, v105, v59
	v_add_f32_e32 v59, v100, v59
	v_add_f32_e32 v59, v101, v59
	s_nop 1
; DI float bflo(unsigned w) { return __uint_as_float(w << 16); }
; DI void finalize_tile(const Params& p, int l, int tile, LAS unsigned char* lds, int tid, int lane, int wave, const bool doq = true) {
;     ...
;         if (doq)
; #pragma unroll
;         for (int h = 0; h < 4; ++h) {
;             bf16_t* qp = QR + t * 768 + h * 192;
;             const u32x4 qa = qa4[h]; const unsigned r1 = r14[h], r2 = r24[h];
;             unpack8(qa, v);
;             const float y1a = bflo(r1) * rcq, y1b = bfhi(r1) * rcq, y2a = bflo(r2) * rcq, y2b = bfhi(r2) * rcq;
;             float ss = (y1a * y1a + y1b * y1b) + (y2a * y2a + y2b * y2b);
; #pragma unroll
;             for (int e = 0; e < 8; ++e) { v[e] *= rcq; ss += v[e] * v[e]; }
;             ss = red16(ss, lane);
;             const float rq = rsqrtf(ss * (1.0f / 192.0f) + EPS) * QSCALE;
;             const f32x4 g0 = qg0, g1 = qg1; const f32x2 gr1 = qgr1, gr2 = qgr2;
;             u32x4 o; o.x = pk2(v[0] * rq * g0.x, v[1] * rq * g0.y); o.y = pk2(v[2] * rq * g0.z, v[3] * rq * g0.w); o.z = pk2(v[4] * rq * g1.x, v[5] * rq * g1.y); o.w = pk2(v[6] * rq * g1.z, v[7] * rq * g1.w);
;             *(u32x4*)(qp + 8 * i) = o;
;             const float a1 = y1a * rq * gr1.x, b1 = y1b * rq * gr1.y, a2 = y2a * rq * gr2.x, b2 = y2b * rq * gr2.y;
;             *(unsigned*)(qp + 128 + 2 * i) = pk2(a1 * cs.x - a2 * sn.x, b1 * cs.y - b2 * sn.y);
;             *(unsigned*)(qp + 160 + 2 * i) = pk2(a1 * sn.x + a2 * cs.x, b1 * sn.y + b2 * cs.y);
;         }
; #pragma unroll
;         for (int h = 0; h < 4; ++h) {
;             const u32x4 ka = ka4[h], va = va4[h];
;             unpack8(ka, v);
;             float ss = 0.f;
; #pragma unroll
;             for (int e = 0; e < 8; ++e) { v[e] *= rckv; ss += v[e] * v[e]; }
;             ss = red16(ss, lane) + s3;
;             const float rk = rsqrtf(ss * (1.0f / 192.0f) + EPS);
;             const f32x4 g0 = kg0, g1 = kg1; const f32x2 gr1 = kgr1, gr2 = kgr2;
;             bf16_t* ko = KB + t * 768 + h * 192;
;             u32x4 o; o.x = pk2(v[0] * rk * g0.x, v[1] * rk * g0.y); o.y = pk2(v[2] * rk * g0.z, v[3] * rk * g0.w); o.z = pk2(v[4] * rk * g1.x, v[5] * rk * g1.y); o.w = pk2(v[6] * rk * g1.z, v[7] * rk * g1.w);
;             *(u32x4*)(ko + 8 * i) = o;
;             const float a1 = x1a * rk * gr1.x, b1 = x1b * rk * gr1.y, a2 = x2a * rk * gr2.x, b2 = x2b * rk * gr2.y;
	v_add_f32_dpp v59, v59, v59 row_ror:1 row_mask:0xf bank_mask:0xf bound_ctrl:1
	s_nop 1
	v_add_f32_dpp v59, v59, v59 row_ror:2 row_mask:0xf bank_mask:0xf bound_ctrl:1
	s_nop 1
	v_add_f32_dpp v59, v59, v59 row_ror:4 row_mask:0xf bank_mask:0xf bound_ctrl:1
	s_nop 1
	v_add_f32_dpp v59, v59, v59 row_ror:8 row_mask:0xf bank_mask:0xf bound_ctrl:1
	v_fmamk_f32 v59, v59, 0x3baaaaab, v228
	v_cmp_gt_f32_e64 s[0:1], s95, v59
	v_mul_f32_e32 v100, 0x4b800000, v59
	s_nop 0
	v_cndmask_b32_e64 v59, v59, v100, s[0:1]
	v_rsq_f32_e32 v59, v59
	s_nop 0
	v_mul_f32_e32 v100, 0x45800000, v59
	v_cndmask_b32_e64 v59, v59, v100, s[0:1]
	v_mul_f32_e32 v100, 0x3dd53b94, v59
	v_pk_mul_f32 v[104:105], v[106:107], v[100:101] op_sel_hi:[1,0]
	s_nop 0
	v_pk_mul_f32 v[46:47], v[46:47], v[104:105]
	v_pk_mul_f32 v[104:105], v[108:109], v[100:101] op_sel_hi:[1,0]
	v_cvt_pk_bf16_f32 v46, v46, v47
	v_pk_mul_f32 v[48:49], v[48:49], v[104:105]
	s_nop 0
	v_cvt_pk_bf16_f32 v47, v48, v49
	v_pk_mul_f32 v[48:49], v[102:103], v[100:101] op_sel_hi:[1,0]
	s_nop 0
	v_pk_mul_f32 v[42:43], v[42:43], v[48:49]
	s_nop 0
	v_cvt_pk_bf16_f32 v48, v42, v43
	v_pk_mul_f32 v[42:43], v[98:99], v[100:101] op_sel_hi:[1,0]
	s_nop 0
	v_pk_mul_f32 v[42:43], v[44:45], v[42:43]
	v_pk_mul_f32 v[44:45], v[96:97], v[100:101] op_sel_hi:[1,0]
	v_cvt_pk_bf16_f32 v49, v42, v43
	v_pk_mul_f32 v[42:43], v[94:95], v[100:101] op_sel_hi:[1,0]
	v_pk_mul_f32 v[44:45], v[88:89], v[44:45]
	flat_store_dwordx4 v[84:85], v[46:49] offset:1152
	v_pk_mul_f32 v[42:43], v[90:91], v[42:43]
	v_lshlrev_b32_e32 v84, 16, v38
	v_pk_mul_f32 v[46:47], v[74:75], v[44:45]
	v_pk_mul_f32 v[44:45], v[72:73], v[44:45]
	v_pk_fma_f32 v[46:47], v[72:73], v[42:43], v[46:47] neg_lo:[0,0,1] neg_hi:[0,0,1]
	v_pk_fma_f32 v[42:43], v[74:75], v[42:43], v[44:45]
	v_cvt_pk_bf16_f32 v46, v46, v47
	v_cvt_pk_bf16_f32 v42, v42, v43
	flat_store_dword v[70:71], v42 offset:1472
	v_cndmask_b32_e32 v42, v87, v132, vcc
	v_lshlrev_b32_e32 v43, 10, v93
	v_lshlrev_b32_e32 v48, 16, v40
	v_and_b32_e32 v49, 0xffff0000, v40
	v_and_b32_e32 v85, 0xffff0000, v38
	flat_store_dword v[70:71], v46 offset:1408
	v_lshlrev_b32_e32 v46, 16, v41
	v_and_b32_e32 v47, 0xffff0000, v41
	v_pk_mul_f32 v[40:41], v[42:43], v[48:49] op_sel_hi:[0,1]
	v_lshlrev_b32_e32 v48, 16, v39
	v_and_b32_e32 v49, 0xffff0000, v39
	v_pk_mul_f32 v[84:85], v[42:43], v[84:85] op_sel_hi:[0,1]
	v_pk_mul_f32 v[48:49], v[42:43], v[48:49] op_sel_hi:[0,1]
	v_pk_mul_f32 v[38:39], v[84:85], v[84:85]
	v_pk_mul_f32 v[94:95], v[48:49], v[48:49]
	v_add_f32_e32 v38, v38, v39
	v_add_f32_e32 v38, v94, v38
	v_pk_mul_f32 v[46:47], v[42:43], v[46:47] op_sel_hi:[0,1]
	v_add_f32_e32 v38, v95, v38
	v_pk_mul_f32 v[90:91], v[46:47], v[46:47]
	v_fmac_f32_e32 v38, v40, v40
	v_pk_fma_f32 v[94:95], v[40:41], v[40:41], v[38:39] op_sel_hi:[1,1,0]
	v_mov_b32_e32 v87, v91
	v_pk_mul_f32 v[90:91], v[76:77], v[76:77]
	v_mov_b32_e32 v96, v76
	v_mov_b32_e32 v97, v46
	v_mov_b32_e32 v94, v91
	v_pk_fma_f32 v[90:91], v[96:97], v[96:97], v[94:95]
	v_add3_u32 v88, 0, v0, v43
	v_pk_add_f32 v[86:87], v[90:91], v[86:87]
	v_mov_b32_e32 v90, v1
	v_mov_b32_e32 v91, v1
	v_mov_b64_e32 v[70:71], s[12:13]
	v_mov_b32_dpp v90, v86 row_ror:1 row_mask:0xf bank_mask:0xf
	v_mov_b32_dpp v91, v87 row_ror:1 row_mask:0xf bank_mask:0xf
	v_pk_add_f32 v[86:87], v[86:87], v[90:91]
	v_mov_b32_e32 v90, v1
	v_mov_b32_e32 v91, v1
	v_mad_i64_i32 v[44:45], s[0:1], v58, s76, v[70:71]
	v_mov_b32_dpp v90, v86 row_ror:2 row_mask:0xf bank_mask:0xf
	v_mov_b32_dpp v91, v87 row_ror:2 row_mask:0xf bank_mask:0xf
	v_pk_add_f32 v[86:87], v[86:87], v[90:91]
	v_mov_b32_e32 v90, v1
	v_mov_b32_e32 v91, v1
	v_lshl_add_u64 v[38:39], v[44:45], 0, v[0:1]
	v_mov_b32_dpp v90, v86 row_ror:4 row_mask:0xf bank_mask:0xf
	v_mov_b32_dpp v91, v87 row_ror:4 row_mask:0xf bank_mask:0xf
	v_pk_add_f32 v[86:87], v[86:87], v[90:91]
	v_mov_b32_e32 v90, v1
	v_mov_b32_e32 v91, v1
	v_lshl_add_u64 v[44:45], v[44:45], 0, v[50:51]
	v_mov_b32_dpp v90, v86 row_ror:8 row_mask:0xf bank_mask:0xf
	v_mov_b32_dpp v91, v87 row_ror:8 row_mask:0xf bank_mask:0xf
	v_pk_add_f32 v[90:91], v[86:87], v[90:91]
	s_nop 0
	v_add_f32_e32 v43, v90, v91
	v_fmamk_f32 v43, v43, 0x3baaaaab, v228
	v_cmp_gt_f32_e32 vcc, s95, v43
	v_mul_f32_e32 v59, 0x4b800000, v43
	s_nop 0
	v_cndmask_b32_e32 v43, v43, v59, vcc
	v_rsq_f32_e32 v43, v43
	s_nop 0
	v_mul_f32_e32 v59, 0x45800000, v43
	v_cndmask_b32_e32 v94, v43, v59, vcc
	v_pk_mul_f32 v[40:41], v[40:41], v[94:95] op_sel_hi:[1,0]
	v_pk_mul_f32 v[84:85], v[84:85], v[94:95] op_sel_hi:[1,0]
	v_pk_mul_f32 v[40:41], v[6:7], v[40:41]
	v_pk_mul_f32 v[48:49], v[48:49], v[94:95] op_sel_hi:[1,0]
	v_cvt_pk_bf16_f32 v86, v40, v41
	v_pk_mul_f32 v[40:41], v[46:47], v[94:95] op_sel_hi:[1,0]
	v_pk_mul_f32 v[46:47], v[94:95], v[78:79] op_sel_hi:[0,1]
	v_pk_mul_f32 v[40:41], v[8:9], v[40:41]
	v_pk_mul_f32 v[84:85], v[10:11], v[84:85]
	v_pk_mul_f32 v[48:49], v[12:13], v[48:49]
	v_cvt_pk_bf16_f32 v87, v40, v41
	v_pk_mul_f32 v[40:41], v[94:95], v[76:77] op_sel_hi:[0,1]
	v_pk_mul_f32 v[46:47], v[80:81], v[46:47]
	v_cvt_pk_bf16_f32 v84, v84, v85
	v_cvt_pk_bf16_f32 v85, v48, v49
	v_pk_mul_f32 v[40:41], v[82:83], v[40:41]
	v_pk_mul_f32 v[48:49], v[74:75], v[46:47]
	v_pk_mul_f32 v[46:47], v[72:73], v[46:47]
	v_pk_fma_f32 v[48:49], v[72:73], v[40:41], v[48:49] neg_lo:[0,0,1] neg_hi:[0,0,1]
	v_pk_fma_f32 v[40:41], v[74:75], v[40:41], v[46:47]
	v_cvt_pk_bf16_f32 v43, v48, v49
	v_cvt_pk_bf16_f32 v40, v40, v41
	flat_store_dword v[44:45], v40 offset:320
	v_lshlrev_b32_e32 v40, 16, v34
	v_and_b32_e32 v41, 0xffff0000, v34
	v_pk_mul_f32 v[40:41], v[42:43], v[40:41] op_sel_hi:[0,1]
	v_cvt_pk_bf16_f32 v34, v40, v41
	v_lshlrev_b32_e32 v40, 16, v35
; #define LAS __attribute__((address_space(3)))
; DI unsigned pk2(float lo, float hi) { f32x2 v = {lo, hi}; return __builtin_bit_cast(unsigned, __builtin_convertvector(v, bf2_t)); }
; DI float red16(float v, int lane) { (void)lane; v += DPP_ROR(v, 1); v += DPP_ROR(v, 2); v += DPP_ROR(v, 4); v += DPP_ROR(v, 8); return v; }
; DI void unpack8(const u32x4 w, float (&v)[8]) { v[0] = bflo(w.x); v[1] = bfhi(w.x); v[2] = bflo(w.y); v[3] = bfhi(w.y); v[4] = bflo(w.z); v[5] = bfhi(w.z); v[6] = bflo(w.w); v[7] = bfhi(w.w); }
; DI void finalize_tile(const Params& p, int l, int tile, LAS unsigned char* lds, int tid, int lane, int wave, const bool doq = true) {
;     ...
; #pragma unroll
;         for (int h = 0; h < 4; ++h) {
;             const u32x4 ka = ka4[h], va = va4[h];
;             unpack8(ka, v);
;             float ss = 0.f;
; #pragma unroll
;             for (int e = 0; e < 8; ++e) { v[e] *= rckv; ss += v[e] * v[e]; }
;             ss = red16(ss, lane) + s3;
;             const float rk = rsqrtf(ss * (1.0f / 192.0f) + EPS);
;             const f32x4 g0 = kg0, g1 = kg1; const f32x2 gr1 = kgr1, gr2 = kgr2;
;             bf16_t* ko = KB + t * 768 + h * 192;
;             u32x4 o; o.x = pk2(v[0] * rk * g0.x, v[1] * rk * g0.y); o.y = pk2(v[2] * rk * g0.z, v[3] * rk * g0.w); o.z = pk2(v[4] * rk * g1.x, v[5] * rk * g1.y); o.w = pk2(v[6] * rk * g1.z, v[7] * rk * g1.w);
;             *(u32x4*)(ko + 8 * i) = o;
;             const float a1 = x1a * rk * gr1.x, b1 = x1b * rk * gr1.y, a2 = x2a * rk * gr2.x, b2 = x2b * rk * gr2.y;
;             *(unsigned*)(ko + 128 + 2 * i) = pk2(a1 * cs.x - a2 * sn.x, b1 * cs.y - b2 * sn.y);
;             *(unsigned*)(ko + 160 + 2 * i) = pk2(a1 * sn.x + a2 * cs.x, b1 * sn.y + b2 * cs.y);
;             unpack8(va, w);
;             u32x4 vo; vo.x = pk2(w[0] * rckv, w[1] * rckv); vo.y = pk2(w[2] * rckv, w[3] * rckv); vo.z = pk2(w[4] * rckv, w[5] * rckv); vo.w = pk2(w[6] * rckv, w[7] * rckv);
;             *(LAS u32x4*)(VL + tl * 512 + h * 128 + 8 * i) = vo;
;         }
	v_and_b32_e32 v41, 0xffff0000, v35
	v_pk_mul_f32 v[40:41], v[42:43], v[40:41] op_sel_hi:[0,1]
	v_cvt_pk_bf16_f32 v35, v40, v41
	v_lshlrev_b32_e32 v40, 16, v36
	v_and_b32_e32 v41, 0xffff0000, v36
	v_pk_mul_f32 v[40:41], v[42:43], v[40:41] op_sel_hi:[0,1]
	v_cvt_pk_bf16_f32 v36, v40, v41
	v_lshlrev_b32_e32 v40, 16, v37
	v_and_b32_e32 v41, 0xffff0000, v37
	flat_store_dwordx4 v[38:39], v[84:87]
	v_pk_mul_f32 v[40:41], v[42:43], v[40:41] op_sel_hi:[0,1]
	v_cvt_pk_bf16_f32 v37, v40, v41
	v_lshlrev_b32_e32 v84, 16, v30
	v_and_b32_e32 v85, 0xffff0000, v30
	v_lshlrev_b32_e32 v46, 16, v31
	v_and_b32_e32 v47, 0xffff0000, v31
	v_pk_mul_f32 v[30:31], v[42:43], v[84:85] op_sel_hi:[0,1]
	flat_store_dword v[44:45], v43 offset:256
	ds_write_b128 v88, v[34:37]
	v_lshlrev_b32_e32 v34, 16, v33
	v_and_b32_e32 v35, 0xffff0000, v33
	v_lshlrev_b32_e32 v40, 16, v32
	v_and_b32_e32 v41, 0xffff0000, v32
	v_pk_mul_f32 v[46:47], v[42:43], v[46:47] op_sel_hi:[0,1]
	v_pk_mul_f32 v[84:85], v[30:31], v[30:31]
	v_pk_mul_f32 v[34:35], v[42:43], v[34:35] op_sel_hi:[0,1]
	v_pk_mul_f32 v[32:33], v[42:43], v[40:41] op_sel_hi:[0,1]
	v_pk_mul_f32 v[48:49], v[46:47], v[46:47]
	v_add_f32_e32 v43, v84, v85
	v_add_f32_e32 v43, v48, v43
	v_pk_mul_f32 v[40:41], v[32:33], v[32:33]
	v_add_f32_e32 v43, v49, v43
	v_add_f32_e32 v40, v40, v43
	v_pk_mul_f32 v[36:37], v[34:35], v[34:35]
	v_add_f32_e32 v40, v41, v40
	v_add_f32_e32 v36, v36, v40
	v_add_f32_e32 v36, v37, v36
	s_nop 1
	v_add_f32_dpp v36, v36, v36 row_ror:1 row_mask:0xf bank_mask:0xf bound_ctrl:1
	s_nop 1
	v_add_f32_dpp v36, v36, v36 row_ror:2 row_mask:0xf bank_mask:0xf bound_ctrl:1
	s_nop 1
	v_add_f32_dpp v36, v36, v36 row_ror:4 row_mask:0xf bank_mask:0xf bound_ctrl:1
	s_nop 1
	v_add_f32_dpp v36, v36, v36 row_ror:8 row_mask:0xf bank_mask:0xf bound_ctrl:1
	v_add_f32_e32 v36, v90, v36
	v_fmamk_f32 v36, v36, 0x3baaaaab, v228
	v_cmp_gt_f32_e32 vcc, s95, v36
	v_mul_f32_e32 v37, 0x4b800000, v36
	s_nop 0
	v_cndmask_b32_e32 v36, v36, v37, vcc
	v_rsq_f32_e32 v36, v36
	s_nop 0
	v_mul_f32_e32 v37, 0x45800000, v36
	v_cndmask_b32_e32 v36, v36, v37, vcc
	v_pk_mul_f32 v[30:31], v[30:31], v[36:37] op_sel_hi:[1,0]
	v_pk_mul_f32 v[40:41], v[46:47], v[36:37] op_sel_hi:[1,0]
	v_pk_mul_f32 v[32:33], v[32:33], v[36:37] op_sel_hi:[1,0]
	v_pk_mul_f32 v[34:35], v[34:35], v[36:37] op_sel_hi:[1,0]
	v_pk_mul_f32 v[30:31], v[10:11], v[30:31]
	v_pk_mul_f32 v[40:41], v[12:13], v[40:41]
	v_pk_mul_f32 v[32:33], v[6:7], v[32:33]
	v_pk_mul_f32 v[34:35], v[8:9], v[34:35]
	v_cvt_pk_bf16_f32 v30, v30, v31
	v_cvt_pk_bf16_f32 v31, v40, v41
	v_cvt_pk_bf16_f32 v32, v32, v33
	v_cvt_pk_bf16_f32 v33, v34, v35
	flat_store_dwordx4 v[38:39], v[30:33] offset:384
	s_nop 1
	v_pk_mul_f32 v[32:33], v[36:37], v[78:79] op_sel_hi:[0,1]
	v_pk_mul_f32 v[30:31], v[36:37], v[76:77] op_sel_hi:[0,1]
	v_pk_mul_f32 v[32:33], v[80:81], v[32:33]
	v_pk_mul_f32 v[30:31], v[82:83], v[30:31]
	v_pk_mul_f32 v[34:35], v[74:75], v[32:33]
	v_pk_mul_f32 v[32:33], v[72:73], v[32:33]
	v_pk_fma_f32 v[34:35], v[72:73], v[30:31], v[34:35] neg_lo:[0,0,1] neg_hi:[0,0,1]
	v_pk_fma_f32 v[30:31], v[74:75], v[30:31], v[32:33]
	v_lshlrev_b32_e32 v36, 16, v22
	v_cvt_pk_bf16_f32 v30, v30, v31
	flat_store_dword v[44:45], v30 offset:704
	v_lshlrev_b32_e32 v30, 16, v26
	v_and_b32_e32 v31, 0xffff0000, v26
	v_pk_mul_f32 v[30:31], v[42:43], v[30:31] op_sel_hi:[0,1]
	v_cvt_pk_bf16_f32 v26, v30, v31
	v_lshlrev_b32_e32 v30, 16, v27
	v_and_b32_e32 v31, 0xffff0000, v27
	v_pk_mul_f32 v[30:31], v[42:43], v[30:31] op_sel_hi:[0,1]
	v_cvt_pk_bf16_f32 v27, v30, v31
	v_lshlrev_b32_e32 v30, 16, v28
	v_and_b32_e32 v31, 0xffff0000, v28
	v_pk_mul_f32 v[30:31], v[42:43], v[30:31] op_sel_hi:[0,1]
	v_and_b32_e32 v37, 0xffff0000, v22
	v_cvt_pk_bf16_f32 v28, v30, v31
	v_lshlrev_b32_e32 v30, 16, v29
	v_and_b32_e32 v31, 0xffff0000, v29
	v_lshlrev_b32_e32 v32, 16, v23
	v_and_b32_e32 v33, 0xffff0000, v23
	v_pk_mul_f32 v[22:23], v[42:43], v[36:37] op_sel_hi:[0,1]
	v_cvt_pk_bf16_f32 v34, v34, v35
	v_pk_mul_f32 v[30:31], v[42:43], v[30:31] op_sel_hi:[0,1]
	v_pk_mul_f32 v[32:33], v[42:43], v[32:33] op_sel_hi:[0,1]
	v_pk_mul_f32 v[36:37], v[22:23], v[22:23]
	flat_store_dword v[44:45], v34 offset:640
	v_cvt_pk_bf16_f32 v29, v30, v31
	v_lshlrev_b32_e32 v30, 16, v24
	v_and_b32_e32 v31, 0xffff0000, v24
	v_pk_mul_f32 v[34:35], v[32:33], v[32:33]
	v_add_f32_e32 v36, v36, v37
	ds_write_b128 v88, v[26:29] offset:256
	v_lshlrev_b32_e32 v26, 16, v25
	v_and_b32_e32 v27, 0xffff0000, v25
	v_pk_mul_f32 v[24:25], v[42:43], v[30:31] op_sel_hi:[0,1]
	v_add_f32_e32 v34, v34, v36
	v_pk_mul_f32 v[30:31], v[24:25], v[24:25]
	v_add_f32_e32 v34, v35, v34
	v_pk_mul_f32 v[26:27], v[42:43], v[26:27] op_sel_hi:[0,1]
	v_add_f32_e32 v30, v30, v34
	v_pk_mul_f32 v[28:29], v[26:27], v[26:27]
	v_add_f32_e32 v30, v31, v30
	v_add_f32_e32 v28, v28, v30
	v_add_f32_e32 v28, v29, v28
	s_nop 1
	v_add_f32_dpp v28, v28, v28 row_ror:1 row_mask:0xf bank_mask:0xf bound_ctrl:1
	s_nop 1
	v_add_f32_dpp v28, v28, v28 row_ror:2 row_mask:0xf bank_mask:0xf bound_ctrl:1
	s_nop 1
	v_add_f32_dpp v28, v28, v28 row_ror:4 row_mask:0xf bank_mask:0xf bound_ctrl:1
	s_nop 1
	v_add_f32_dpp v28, v28, v28 row_ror:8 row_mask:0xf bank_mask:0xf bound_ctrl:1
	v_add_f32_e32 v28, v90, v28
	v_fmamk_f32 v28, v28, 0x3baaaaab, v228
	v_cmp_gt_f32_e32 vcc, s95, v28
	v_mul_f32_e32 v29, 0x4b800000, v28
	s_nop 0
	v_cndmask_b32_e32 v28, v28, v29, vcc
	v_rsq_f32_e32 v28, v28
	s_nop 0
	v_mul_f32_e32 v29, 0x45800000, v28
	v_cndmask_b32_e32 v28, v28, v29, vcc
	v_pk_mul_f32 v[22:23], v[22:23], v[28:29] op_sel_hi:[1,0]
	v_pk_mul_f32 v[30:31], v[32:33], v[28:29] op_sel_hi:[1,0]
	v_pk_mul_f32 v[24:25], v[24:25], v[28:29] op_sel_hi:[1,0]
; #define LAS __attribute__((address_space(3)))
; DI unsigned pk2(float lo, float hi) { f32x2 v = {lo, hi}; return __builtin_bit_cast(unsigned, __builtin_convertvector(v, bf2_t)); }
; DI float red16(float v, int lane) { (void)lane; v += DPP_ROR(v, 1); v += DPP_ROR(v, 2); v += DPP_ROR(v, 4); v += DPP_ROR(v, 8); return v; }
; DI void unpack8(const u32x4 w, float (&v)[8]) { v[0] = bflo(w.x); v[1] = bfhi(w.x); v[2] = bflo(w.y); v[3] = bfhi(w.y); v[4] = bflo(w.z); v[5] = bfhi(w.z); v[6] = bflo(w.w); v[7] = bfhi(w.w); }
; DI void finalize_tile(const Params& p, int l, int tile, LAS unsigned char* lds, int tid, int lane, int wave, const bool doq = true) {
;     ...
; #pragma unroll
;         for (int h = 0; h < 4; ++h) {
;             const u32x4 ka = ka4[h], va = va4[h];
;             unpack8(ka, v);
;             float ss = 0.f;
; #pragma unroll
;             for (int e = 0; e < 8; ++e) { v[e] *= rckv; ss += v[e] * v[e]; }
;             ss = red16(ss, lane) + s3;
;             const float rk = rsqrtf(ss * (1.0f / 192.0f) + EPS);
;             const f32x4 g0 = kg0, g1 = kg1; const f32x2 gr1 = kgr1, gr2 = kgr2;
;             bf16_t* ko = KB + t * 768 + h * 192;
;             u32x4 o; o.x = pk2(v[0] * rk * g0.x, v[1] * rk * g0.y); o.y = pk2(v[2] * rk * g0.z, v[3] * rk * g0.w); o.z = pk2(v[4] * rk * g1.x, v[5] * rk * g1.y); o.w = pk2(v[6] * rk * g1.z, v[7] * rk * g1.w);
;             *(u32x4*)(ko + 8 * i) = o;
;             const float a1 = x1a * rk * gr1.x, b1 = x1b * rk * gr1.y, a2 = x2a * rk * gr2.x, b2 = x2b * rk * gr2.y;
;             *(unsigned*)(ko + 128 + 2 * i) = pk2(a1 * cs.x - a2 * sn.x, b1 * cs.y - b2 * sn.y);
;             *(unsigned*)(ko + 160 + 2 * i) = pk2(a1 * sn.x + a2 * cs.x, b1 * sn.y + b2 * cs.y);
;             unpack8(va, w);
;             u32x4 vo; vo.x = pk2(w[0] * rckv, w[1] * rckv); vo.y = pk2(w[2] * rckv, w[3] * rckv); vo.z = pk2(w[4] * rckv, w[5] * rckv); vo.w = pk2(w[6] * rckv, w[7] * rckv);
;             *(LAS u32x4*)(VL + tl * 512 + h * 128 + 8 * i) = vo;
;         }
;     }
	v_pk_mul_f32 v[26:27], v[26:27], v[28:29] op_sel_hi:[1,0]
	v_pk_mul_f32 v[22:23], v[10:11], v[22:23]
	v_pk_mul_f32 v[30:31], v[12:13], v[30:31]
	v_pk_mul_f32 v[24:25], v[6:7], v[24:25]
	v_pk_mul_f32 v[26:27], v[8:9], v[26:27]
	v_cvt_pk_bf16_f32 v22, v22, v23
	v_cvt_pk_bf16_f32 v23, v30, v31
	v_cvt_pk_bf16_f32 v24, v24, v25
	v_cvt_pk_bf16_f32 v25, v26, v27
	flat_store_dwordx4 v[38:39], v[22:25] offset:768
	s_nop 1
	v_pk_mul_f32 v[24:25], v[28:29], v[78:79] op_sel_hi:[0,1]
	v_pk_mul_f32 v[22:23], v[28:29], v[76:77] op_sel_hi:[0,1]
	v_pk_mul_f32 v[24:25], v[80:81], v[24:25]
	v_pk_mul_f32 v[22:23], v[82:83], v[22:23]
	v_pk_mul_f32 v[26:27], v[74:75], v[24:25]
	v_pk_mul_f32 v[24:25], v[72:73], v[24:25]
	v_pk_fma_f32 v[26:27], v[72:73], v[22:23], v[26:27] neg_lo:[0,0,1] neg_hi:[0,0,1]
	v_pk_fma_f32 v[22:23], v[74:75], v[22:23], v[24:25]
	v_lshlrev_b32_e32 v28, 16, v14
	v_cvt_pk_bf16_f32 v22, v22, v23
	flat_store_dword v[44:45], v22 offset:1088
	v_lshlrev_b32_e32 v22, 16, v18
	v_and_b32_e32 v23, 0xffff0000, v18
	v_pk_mul_f32 v[22:23], v[42:43], v[22:23] op_sel_hi:[0,1]
	v_cvt_pk_bf16_f32 v18, v22, v23
	v_lshlrev_b32_e32 v22, 16, v19
	v_and_b32_e32 v23, 0xffff0000, v19
	v_pk_mul_f32 v[22:23], v[42:43], v[22:23] op_sel_hi:[0,1]
	v_cvt_pk_bf16_f32 v19, v22, v23
	v_lshlrev_b32_e32 v22, 16, v20
	v_and_b32_e32 v23, 0xffff0000, v20
	v_pk_mul_f32 v[22:23], v[42:43], v[22:23] op_sel_hi:[0,1]
	v_and_b32_e32 v29, 0xffff0000, v14
	v_cvt_pk_bf16_f32 v20, v22, v23
	v_lshlrev_b32_e32 v22, 16, v21
	v_and_b32_e32 v23, 0xffff0000, v21
	v_lshlrev_b32_e32 v24, 16, v15
	v_and_b32_e32 v25, 0xffff0000, v15
	v_pk_mul_f32 v[14:15], v[42:43], v[28:29] op_sel_hi:[0,1]
	v_cvt_pk_bf16_f32 v26, v26, v27
	v_pk_mul_f32 v[22:23], v[42:43], v[22:23] op_sel_hi:[0,1]
	v_pk_mul_f32 v[24:25], v[42:43], v[24:25] op_sel_hi:[0,1]
	v_pk_mul_f32 v[28:29], v[14:15], v[14:15]
	flat_store_dword v[44:45], v26 offset:1024
	v_cvt_pk_bf16_f32 v21, v22, v23
	v_lshlrev_b32_e32 v22, 16, v16
	v_and_b32_e32 v23, 0xffff0000, v16
	v_pk_mul_f32 v[26:27], v[24:25], v[24:25]
	v_add_f32_e32 v28, v28, v29
	ds_write_b128 v88, v[18:21] offset:512
	v_lshlrev_b32_e32 v18, 16, v17
	v_and_b32_e32 v19, 0xffff0000, v17
	v_pk_mul_f32 v[16:17], v[42:43], v[22:23] op_sel_hi:[0,1]
	v_add_f32_e32 v26, v26, v28
	v_pk_mul_f32 v[22:23], v[16:17], v[16:17]
	v_add_f32_e32 v26, v27, v26
	v_pk_mul_f32 v[18:19], v[42:43], v[18:19] op_sel_hi:[0,1]
	v_add_f32_e32 v22, v22, v26
	v_pk_mul_f32 v[20:21], v[18:19], v[18:19]
	v_add_f32_e32 v22, v23, v22
	v_add_f32_e32 v20, v20, v22
	v_add_f32_e32 v20, v21, v20
	s_nop 1
	v_add_f32_dpp v20, v20, v20 row_ror:1 row_mask:0xf bank_mask:0xf bound_ctrl:1
	s_nop 1
	v_add_f32_dpp v20, v20, v20 row_ror:2 row_mask:0xf bank_mask:0xf bound_ctrl:1
	s_nop 1
	v_add_f32_dpp v20, v20, v20 row_ror:4 row_mask:0xf bank_mask:0xf bound_ctrl:1
	s_nop 1
	v_add_f32_dpp v20, v20, v20 row_ror:8 row_mask:0xf bank_mask:0xf bound_ctrl:1
	v_add_f32_e32 v20, v90, v20
	v_fmamk_f32 v20, v20, 0x3baaaaab, v228
	v_cmp_gt_f32_e32 vcc, s95, v20
	v_mul_f32_e32 v21, 0x4b800000, v20
	s_nop 0
	v_cndmask_b32_e32 v20, v20, v21, vcc
	v_rsq_f32_e32 v20, v20
	s_nop 0
	v_mul_f32_e32 v21, 0x45800000, v20
	v_cndmask_b32_e32 v20, v20, v21, vcc
	v_pk_mul_f32 v[14:15], v[14:15], v[20:21] op_sel_hi:[1,0]
	s_nop 0
	v_pk_mul_f32 v[10:11], v[10:11], v[14:15]
	v_pk_mul_f32 v[14:15], v[24:25], v[20:21] op_sel_hi:[1,0]
	v_cvt_pk_bf16_f32 v10, v10, v11
	v_pk_mul_f32 v[12:13], v[12:13], v[14:15]
	s_nop 0
	v_cvt_pk_bf16_f32 v11, v12, v13
	v_pk_mul_f32 v[12:13], v[16:17], v[20:21] op_sel_hi:[1,0]
	s_nop 0
	v_pk_mul_f32 v[6:7], v[6:7], v[12:13]
	s_nop 0
	v_cvt_pk_bf16_f32 v12, v6, v7
	v_pk_mul_f32 v[6:7], v[18:19], v[20:21] op_sel_hi:[1,0]
	s_nop 0
	v_pk_mul_f32 v[6:7], v[8:9], v[6:7]
	v_pk_mul_f32 v[8:9], v[20:21], v[78:79] op_sel_hi:[0,1]
	v_cvt_pk_bf16_f32 v13, v6, v7
	v_pk_mul_f32 v[6:7], v[20:21], v[76:77] op_sel_hi:[0,1]
	v_pk_mul_f32 v[8:9], v[80:81], v[8:9]
	flat_store_dwordx4 v[38:39], v[10:13] offset:1152
	v_pk_mul_f32 v[6:7], v[82:83], v[6:7]
	s_nop 0
	v_pk_mul_f32 v[10:11], v[74:75], v[8:9]
	v_pk_mul_f32 v[8:9], v[72:73], v[8:9]
	v_pk_fma_f32 v[10:11], v[72:73], v[6:7], v[10:11] neg_lo:[0,0,1] neg_hi:[0,0,1]
	v_pk_fma_f32 v[6:7], v[74:75], v[6:7], v[8:9]
	v_add_u32_e32 v72, 4, v58
	v_cvt_pk_bf16_f32 v6, v6, v7
	flat_store_dword v[44:45], v6 offset:1472
	v_lshlrev_b32_e32 v6, 16, v2
	v_and_b32_e32 v7, 0xffff0000, v2
	v_pk_mul_f32 v[6:7], v[42:43], v[6:7] op_sel_hi:[0,1]
	v_cvt_pk_bf16_f32 v2, v6, v7
	v_lshlrev_b32_e32 v6, 16, v3
	v_and_b32_e32 v7, 0xffff0000, v3
	v_pk_mul_f32 v[6:7], v[42:43], v[6:7] op_sel_hi:[0,1]
	v_cvt_pk_bf16_f32 v3, v6, v7
	v_lshlrev_b32_e32 v6, 16, v4
	v_and_b32_e32 v7, 0xffff0000, v4
	v_pk_mul_f32 v[6:7], v[42:43], v[6:7] op_sel_hi:[0,1]
	v_cvt_pk_bf16_f32 v4, v6, v7
	v_lshlrev_b32_e32 v6, 16, v5
	v_and_b32_e32 v7, 0xffff0000, v5
	v_cvt_pk_bf16_f32 v10, v10, v11
	v_pk_mul_f32 v[6:7], v[42:43], v[6:7] op_sel_hi:[0,1]
	v_ashrrev_i32_e32 v73, 31, v72
	flat_store_dword v[44:45], v10 offset:1408
	v_cvt_pk_bf16_f32 v5, v6, v7
	v_lshlrev_b64 v[10:11], 9, v[72:73]
	ds_write_b128 v88, v[2:5] offset:768
	v_lshl_add_u64 v[6:7], v[52:53], 0, v[10:11]
	s_cmp_lg_u32 s98, 0
	s_cbranch_scc1 .Lfin_done
	s_mov_b32 s98, 1
	v_mov_b32_e32 v58, v72
	v_mov_b32_e32 v59, v73
	v_and_b32_e32 v16, 15, v92
	v_add_u32_e32 v93, 4, v93
	s_sub_i32 s22, s22, s68
	s_branch .Lfin_P
; DI void finalize_tile(const Params& p, int l, int tile, LAS unsigned char* lds, int tid, int lane, int wave, const bool doq = true) {
;     ...
;     __syncthreads();
;     {
;         const int b = t0 >> 12, s0 = t0 & 4095, h = tid >> 7, dv = tid & 127;
;         bf16_t* dst = VT + ((size_t)((b * 4 + h) * 128 + dv)) * SEQ + s0;
; #pragma unroll
;         for (int q = 0; q < 8; ++q) { unsigned wv[4];
; #pragma unroll
;             for (int e = 0; e < 4; ++e) wv[e] = (unsigned)VL[(q * 8 + 2 * e) * 512 + tid] | ((unsigned)VL[(q * 8 + 2 * e + 1) * 512 + tid] << 16);
;             *(u32x4*)(dst + q * 8) = (u32x4){wv[0], wv[1], wv[2], wv[3]}; }
;     }
;     __syncthreads();
.Lfin_done:
	s_and_b32 s1, s18, 0xfffffe00
	s_and_b32 s0, s19, 0xfc0
	s_lshl_b32 s92, s0, 1
	s_add_i32 s19, s19, s37
	s_add_i32 s18, s18, s97
	s_cmpk_gt_i32 s22, 0xff
	v_add_u32_e32 v2, s1, v92
	v_ashrrev_i32_e32 v3, 31, v2
	v_lshlrev_b64 v[2:3], 13, v[2:3]
	v_lshl_add_u64 v[2:3], s[6:7], 0, v[2:3]
	v_lshl_add_u32 v0, v92, 1, 0
	s_waitcnt lgkmcnt(0)
	s_barrier
	v_lshl_add_u64 v[6:7], v[2:3], 0, s[92:93]
	s_mov_b64 s[0:1], 0xe600000
	v_lshl_add_u64 v[8:9], v[6:7], 0, s[0:1]
	s_mov_b32 s0, 0xe600000
	v_add_co_u32_e32 v6, vcc, s0, v6
	v_addc_co_u32_e32 v7, vcc, 0, v7, vcc
	ds_read_u16 v2, v0
	ds_read_u16 v10, v0 offset:1024
	ds_read_u16 v3, v0 offset:2048
	ds_read_u16 v11, v0 offset:3072
	ds_read_u16 v4, v0 offset:4096
	ds_read_u16 v12, v0 offset:5120
	ds_read_u16 v5, v0 offset:6144
	ds_read_u16 v13, v0 offset:7168
	s_waitcnt lgkmcnt(0)
	v_lshl_or_b32 v2, v10, 16, v2
	v_lshl_or_b32 v3, v11, 16, v3
	v_lshl_or_b32 v4, v12, 16, v4
	v_lshl_or_b32 v5, v13, 16, v5
	flat_store_dwordx4 v[6:7], v[2:5]
	ds_read_u16 v2, v0 offset:8192
	ds_read_u16 v10, v0 offset:9216
	ds_read_u16 v3, v0 offset:10240
	ds_read_u16 v11, v0 offset:11264
	ds_read_u16 v4, v0 offset:12288
	ds_read_u16 v12, v0 offset:13312
	ds_read_u16 v5, v0 offset:14336
	ds_read_u16 v13, v0 offset:15360
	s_waitcnt lgkmcnt(0)
	v_lshl_or_b32 v2, v10, 16, v2
	v_lshl_or_b32 v3, v11, 16, v3
	v_lshl_or_b32 v4, v12, 16, v4
	v_lshl_or_b32 v5, v13, 16, v5
	flat_store_dwordx4 v[8:9], v[2:5] offset:16
	ds_read_u16 v2, v0 offset:16384
	ds_read_u16 v10, v0 offset:17408
	ds_read_u16 v3, v0 offset:18432
	ds_read_u16 v11, v0 offset:19456
	ds_read_u16 v4, v0 offset:20480
	ds_read_u16 v12, v0 offset:21504
	ds_read_u16 v5, v0 offset:22528
	ds_read_u16 v13, v0 offset:23552
	s_waitcnt lgkmcnt(0)
	v_lshl_or_b32 v2, v10, 16, v2
	v_lshl_or_b32 v3, v11, 16, v3
	v_lshl_or_b32 v4, v12, 16, v4
	v_lshl_or_b32 v5, v13, 16, v5
	flat_store_dwordx4 v[8:9], v[2:5] offset:32
	ds_read_u16 v2, v0 offset:24576
	ds_read_u16 v10, v0 offset:25600
	ds_read_u16 v3, v0 offset:26624
	ds_read_u16 v11, v0 offset:27648
	ds_read_u16 v4, v0 offset:28672
	ds_read_u16 v12, v0 offset:29696
	ds_read_u16 v5, v0 offset:30720
	ds_read_u16 v13, v0 offset:31744
	s_waitcnt lgkmcnt(0)
	v_lshl_or_b32 v2, v10, 16, v2
	v_lshl_or_b32 v3, v11, 16, v3
	v_lshl_or_b32 v4, v12, 16, v4
	v_lshl_or_b32 v5, v13, 16, v5
	flat_store_dwordx4 v[8:9], v[2:5] offset:48
	ds_read_u16 v2, v0 offset:32768
	ds_read_u16 v10, v0 offset:33792
	ds_read_u16 v3, v0 offset:34816
	ds_read_u16 v11, v0 offset:35840
	ds_read_u16 v4, v0 offset:36864
	ds_read_u16 v12, v0 offset:37888
	ds_read_u16 v5, v0 offset:38912
	ds_read_u16 v13, v0 offset:39936
	s_waitcnt lgkmcnt(0)
	v_lshl_or_b32 v2, v10, 16, v2
	v_lshl_or_b32 v3, v11, 16, v3
	v_lshl_or_b32 v4, v12, 16, v4
	v_lshl_or_b32 v5, v13, 16, v5
	flat_store_dwordx4 v[8:9], v[2:5] offset:64
	ds_read_u16 v2, v0 offset:40960
	ds_read_u16 v10, v0 offset:41984
	ds_read_u16 v3, v0 offset:43008
	ds_read_u16 v11, v0 offset:44032
	ds_read_u16 v4, v0 offset:45056
	ds_read_u16 v12, v0 offset:46080
	ds_read_u16 v5, v0 offset:47104
	ds_read_u16 v13, v0 offset:48128
	s_waitcnt lgkmcnt(0)
	v_lshl_or_b32 v2, v10, 16, v2
	v_lshl_or_b32 v3, v11, 16, v3
	v_lshl_or_b32 v4, v12, 16, v4
	v_lshl_or_b32 v5, v13, 16, v5
	flat_store_dwordx4 v[8:9], v[2:5] offset:80
	ds_read_u16 v2, v0 offset:49152
	ds_read_u16 v10, v0 offset:50176
	ds_read_u16 v3, v0 offset:51200
	ds_read_u16 v11, v0 offset:52224
	ds_read_u16 v4, v0 offset:53248
	ds_read_u16 v12, v0 offset:54272
	ds_read_u16 v5, v0 offset:55296
	ds_read_u16 v13, v0 offset:56320
	s_waitcnt lgkmcnt(0)
	v_lshl_or_b32 v2, v10, 16, v2
	v_lshl_or_b32 v3, v11, 16, v3
	v_lshl_or_b32 v4, v12, 16, v4
	v_lshl_or_b32 v5, v13, 16, v5
	flat_store_dwordx4 v[8:9], v[2:5] offset:96
	ds_read_u16 v2, v0 offset:57344
	ds_read_u16 v10, v0 offset:58368
	ds_read_u16 v3, v0 offset:59392
	ds_read_u16 v11, v0 offset:60416
	ds_read_u16 v4, v0 offset:61440
	ds_read_u16 v12, v0 offset:62464
	ds_read_u16 v5, v0 offset:63488
	ds_read_u16 v13, v0 offset:64512
	s_waitcnt lgkmcnt(0)
	v_lshl_or_b32 v2, v10, 16, v2
	v_lshl_or_b32 v3, v11, 16, v3
	v_lshl_or_b32 v4, v12, 16, v4
	v_lshl_or_b32 v5, v13, 16, v5
	flat_store_dwordx4 v[8:9], v[2:5] offset:112
	s_waitcnt lgkmcnt(0)
	s_barrier
	s_cbranch_scc0 .LBB0_366
